# norm phases (N1,N2,final): per-row g/scale/shift loads issued up front instead of load/wait/store ladder; g_final hoisted out of loop; X3 output loads hoisted
# speedup vs baseline: 1.0147x; 1.0029x over previous
; __device__ __forceinline__ unsigned pk2(float lo, float hi) { f32x2 v = {lo, hi}; bf16x2_t b = __builtin_convertvector(v, bf16x2_t); return __builtin_bit_cast(unsigned, b); }
; __device__ __forceinline__ void norm_rows(const float* srcL, const float* srcC, const float* g, const float* mv, int sc_idx, int sh_idx, bf16* out, int nrows, int gw, int NGW, int lane, const float* part, int nsplit, float* wb) {
;     for (int row = gw; row < nrows; row += NGW) {
;         const bool isc = row >= ML;
;         const f32x4* src = (const f32x4*)(isc ? srcC + (size_t)(row - ML) * DM : srcL + (size_t)row * DM) + lane;
;         const float* mvv = mv + (isc ? 2 : (row >> 13)) * ADA;
;         f32x4 v[8]; float s = 0.f;
; #pragma unroll
;         for (int j = 0; j < 8; ++j) v[j] = src[64 * j];
;         if (isc && nsplit > 0) {
;             const f32x4* pp = (const f32x4*)(part + (size_t)(row - ML) * DM) + lane;
; #pragma unroll 4
;             for (int sp = 0; sp < nsplit; ++sp) {
; #pragma unroll
;                 for (int j = 0; j < 8; ++j) v[j] += pp[(size_t)sp * (MC * DM / 4) + 64 * j];
;             }
;             if (wb) { f32x4* w4 = (f32x4*)(wb + (size_t)(row - ML) * DM) + lane;
; #pragma unroll
;                 for (int j = 0; j < 8; ++j) w4[64 * j] = v[j]; }
;         }
; #pragma unroll
;         for (int j = 0; j < 8; ++j) s += (v[j].x * v[j].x + v[j].y * v[j].y) + (v[j].z * v[j].z + v[j].w * v[j].w);
;         const float rstd = 1.f / sqrtf(wave_sum(s) * (1.f / DM) + 1e-6f);
;         u32x2* o = (u32x2*)(out + (size_t)row * DM) + lane;
; #pragma unroll
;         for (int j = 0; j < 8; ++j) {
;             const int col = 4 * (lane + 64 * j);
;             const f32x4 gg = *(const f32x4*)(g + col), sc = *(const f32x4*)(mvv + sc_idx * DM + col), sh = *(const f32x4*)(mvv + sh_idx * DM + col);
;             const f32x4 y = (v[j] * rstd) * gg * (sc + 1.f) + sh;
;             u32x2 w; w.x = pk2(y.x, y.y); w.y = pk2(y.z, y.w); o[64 * j] = w;
;         }
.LBB0_252:
	s_min_i32 s4, s10, 0x4000
	s_ashr_i32 s4, s4, 13
	s_mul_i32 s22, s4, 0x3000
	s_ashr_i32 s23, s22, 31
	s_lshl_b64 s[22:23], s[22:23], 2
	s_add_u32 s22, s6, s22
	s_addc_u32 s23, s7, s23
	s_lshl_b64 s[40:41], s[10:11], 12
	s_add_u32 s26, s22, 0x2000
	s_addc_u32 s27, s23, 0
	global_load_dwordx4 v[120:123], v[36:37], off
	global_load_dwordx4 v[124:127], v58, s[26:27]
	global_load_dwordx4 v[128:131], v58, s[22:23]
	global_load_dwordx4 v[132:135], v[36:37], off offset:1024
	global_load_dwordx4 v[136:139], v59, s[26:27]
	global_load_dwordx4 v[140:143], v58, s[22:23] offset:1024
	global_load_dwordx4 v[150:153], v[36:37], off offset:2048
	global_load_dwordx4 v[154:157], v60, s[26:27]
	global_load_dwordx4 v[158:161], v58, s[22:23] offset:2048
	global_load_dwordx4 v[162:165], v[36:37], off offset:3072
	global_load_dwordx4 v[174:177], v61, s[26:27]
	global_load_dwordx4 v[178:181], v58, s[22:23] offset:3072
	global_load_dwordx4 v[182:185], v[38:39], off
	global_load_dwordx4 v[186:189], v62, s[26:27]
	global_load_dwordx4 v[190:193], v62, s[22:23]
	global_load_dwordx4 v[194:197], v[40:41], off
	global_load_dwordx4 v[198:201], v63, s[26:27]
	global_load_dwordx4 v[202:205], v63, s[22:23]
	global_load_dwordx4 v[206:209], v[42:43], off
	global_load_dwordx4 v[210:213], v64, s[26:27]
	global_load_dwordx4 v[214:217], v64, s[22:23]
	global_load_dwordx4 v[218:221], v[44:45], off
	global_load_dwordx4 v[222:225], v65, s[26:27]
	global_load_dwordx4 v[226:229], v65, s[22:23]
	s_waitcnt vmcnt(31)
	v_pk_mul_f32 v[76:77], v[28:29], v[28:29]
	s_waitcnt vmcnt(30)
	v_pk_mul_f32 v[78:79], v[16:17], v[16:17]
	v_pk_mul_f32 v[72:73], v[30:31], v[30:31]
	v_pk_mul_f32 v[74:75], v[18:19], v[18:19]
	v_mov_b32_e32 v80, v76
	v_mov_b32_e32 v81, v78
	v_mov_b32_e32 v78, v77
	s_waitcnt vmcnt(29)
	v_pk_mul_f32 v[68:69], v[10:11], v[10:11]
	v_pk_mul_f32 v[70:71], v[8:9], v[8:9]
	v_pk_add_f32 v[76:77], v[80:81], v[78:79]
	v_mov_b32_e32 v78, v72
	v_mov_b32_e32 v79, v74
	v_mov_b32_e32 v74, v73
	v_pk_add_f32 v[72:73], v[78:79], v[74:75]
	v_pk_mov_b32 v[74:75], v[70:71], v[68:69] op_sel:[1,0]
	v_mov_b32_e32 v71, v69
	v_pk_add_f32 v[68:69], v[74:75], v[70:71]
	v_pk_add_f32 v[72:73], v[76:77], v[72:73]
	v_pk_add_f32 v[68:69], v[68:69], v[68:69] op_sel_hi:[0,1]
	s_waitcnt vmcnt(28)
	v_mul_f32_e32 v68, v0, v0
	v_pk_fma_f32 v[70:71], v[0:1], v[0:1], v[68:69] op_sel_hi:[1,1,0]
	v_mul_f32_e32 v68, v2, v2
	v_pk_add_f32 v[72:73], v[72:73], v[72:73] op_sel_hi:[0,1]
	v_pk_fma_f32 v[74:75], v[2:3], v[2:3], v[68:69] op_sel_hi:[1,1,0]
	s_waitcnt vmcnt(27)
	v_mul_f32_e32 v70, v24, v24
	v_mul_f32_e32 v74, v25, v25
	v_mul_f32_e32 v68, v26, v26
	v_mul_f32_e32 v72, v27, v27
	s_waitcnt vmcnt(26)
	v_pk_mul_f32 v[50:51], v[22:23], v[22:23]
	v_pk_mul_f32 v[66:67], v[20:21], v[20:21]
	v_pk_add_f32 v[70:71], v[70:71], v[74:75]
	v_pk_add_f32 v[68:69], v[68:69], v[72:73]
	v_pk_add_f32 v[68:69], v[70:71], v[68:69]
	v_pk_mov_b32 v[70:71], v[66:67], v[50:51] op_sel:[1,0]
	v_mov_b32_e32 v67, v51
	v_pk_add_f32 v[50:51], v[70:71], v[66:67]
	v_pk_add_f32 v[50:51], v[50:51], v[50:51] op_sel_hi:[0,1]
	s_waitcnt vmcnt(25)
	v_mul_f32_e32 v50, v12, v12
	v_pk_fma_f32 v[66:67], v[12:13], v[12:13], v[50:51] op_sel_hi:[1,1,0]
	v_mul_f32_e32 v50, v14, v14
	v_pk_add_f32 v[68:69], v[68:69], v[68:69] op_sel_hi:[0,1]
	v_pk_fma_f32 v[70:71], v[14:15], v[14:15], v[50:51] op_sel_hi:[1,1,0]
	s_waitcnt vmcnt(24)
	v_mul_f32_e32 v66, v4, v4
	v_mul_f32_e32 v70, v5, v5
	v_mul_f32_e32 v50, v6, v6
	v_mul_f32_e32 v68, v7, v7
	v_pk_add_f32 v[66:67], v[66:67], v[70:71]
	v_pk_add_f32 v[50:51], v[50:51], v[68:69]
	v_pk_add_f32 v[50:51], v[66:67], v[50:51]
	v_add_f32_e32 v50, v50, v51
	ds_bpermute_b32 v51, v52, v50
	s_add_i32 s10, s10, s88
	s_add_i32 s24, s24, s88
	s_cmpk_lt_i32 s10, 0x4200
	s_waitcnt lgkmcnt(0)
	v_add_f32_e32 v50, v50, v51
	ds_bpermute_b32 v51, v53, v50
	s_waitcnt lgkmcnt(0)
	v_add_f32_e32 v50, v50, v51
	ds_bpermute_b32 v51, v54, v50
	s_waitcnt lgkmcnt(0)
	v_add_f32_e32 v50, v50, v51
	ds_bpermute_b32 v51, v55, v50
	s_waitcnt lgkmcnt(0)
	v_add_f32_e32 v50, v50, v51
	ds_bpermute_b32 v51, v56, v50
	s_waitcnt lgkmcnt(0)
	v_add_f32_e32 v50, v50, v51
	ds_bpermute_b32 v51, v57, v50
	s_waitcnt lgkmcnt(0)
	v_add_f32_e32 v50, v50, v51
	v_fmamk_f32 v50, v50, 0x3a000000, v167
	v_mul_f32_e32 v51, 0x4f800000, v50
	v_cmp_gt_f32_e32 vcc, s72, v50
	s_nop 1
	v_cndmask_b32_e32 v50, v50, v51, vcc
	v_sqrt_f32_e32 v51, v50
	s_nop 0
	v_add_u32_e32 v78, -1, v51
	v_fma_f32 v79, -v78, v51, v50
	v_cmp_ge_f32_e64 s[38:39], 0, v79
	v_add_u32_e32 v79, 1, v51
	s_nop 0
	v_cndmask_b32_e64 v78, v51, v78, s[38:39]
	v_fma_f32 v51, -v79, v51, v50
	v_cmp_lt_f32_e64 s[38:39], 0, v51
	s_nop 1
	v_cndmask_b32_e64 v51, v78, v79, s[38:39]
	v_mul_f32_e32 v78, 0x37800000, v51
	v_cndmask_b32_e32 v51, v51, v78, vcc
	v_cmp_class_f32_e32 vcc, v50, v168
	s_nop 1
	v_cndmask_b32_e32 v50, v51, v50, vcc
	v_div_scale_f32 v51, s[38:39], v50, v50, 1.0
	v_rcp_f32_e32 v78, v51
	s_nop 0
	v_fma_f32 v79, -v51, v78, 1.0
	v_fmac_f32_e32 v78, v79, v78
	v_div_scale_f32 v79, vcc, 1.0, v50, 1.0
	v_mul_f32_e32 v80, v79, v78
	v_fma_f32 v81, -v51, v80, v79
	v_fmac_f32_e32 v80, v81, v78
	v_fma_f32 v51, -v51, v80, v79
	v_div_fmas_f32 v51, v51, v78, v80
	v_div_fixup_f32 v50, v51, v50, 1.0
	v_pk_mul_f32 v[30:31], v[30:31], v[50:51] op_sel_hi:[1, 0]
	v_pk_mul_f32 v[28:29], v[28:29], v[50:51] op_sel_hi:[1, 0]
	s_waitcnt vmcnt(0)
; __device__ __forceinline__ unsigned pk2(float lo, float hi) { f32x2 v = {lo, hi}; bf16x2_t b = __builtin_convertvector(v, bf16x2_t); return __builtin_bit_cast(unsigned, b); }
; __device__ __forceinline__ void norm_rows(const float* srcL, const float* srcC, const float* g, const float* mv, int sc_idx, int sh_idx, bf16* out, int nrows, int gw, int NGW, int lane, const float* part, int nsplit, float* wb) {
;     ...
;         u32x2* o = (u32x2*)(out + (size_t)row * DM) + lane;
; #pragma unroll
;         for (int j = 0; j < 8; ++j) {
;             const int col = 4 * (lane + 64 * j);
;             const f32x4 gg = *(const f32x4*)(g + col), sc = *(const f32x4*)(mvv + sc_idx * DM + col), sh = *(const f32x4*)(mvv + sh_idx * DM + col);
;             const f32x4 y = (v[j] * rstd) * gg * (sc + 1.f) + sh;
;             u32x2 w; w.x = pk2(y.x, y.y); w.y = pk2(y.z, y.w); o[64 * j] = w;
;         }
	v_pk_mul_f32 v[30:31], v[122:123], v[30:31]
	v_pk_mul_f32 v[28:29], v[120:121], v[28:29]
	v_pk_add_f32 v[66:67], v[126:127], 1.0 op_sel_hi:[1, 0]
	v_pk_add_f32 v[68:69], v[124:125], 1.0 op_sel_hi:[1, 0]
	v_pk_fma_f32 v[30:31], v[66:67], v[30:31], v[130:131]
	v_pk_fma_f32 v[28:29], v[68:69], v[28:29], v[128:129]
	v_lshl_add_u64 v[78:79], v[32:33], 0, s[40:41]
	v_cvt_pk_bf16_f32 v28, v28, v29
	v_cvt_pk_bf16_f32 v29, v30, v31
	global_store_dwordx2 v[78:79], v[28:29], off
	s_nop 0
	v_pk_mul_f32 v[18:19], v[18:19], v[50:51] op_sel_hi:[1, 0]
	v_pk_mul_f32 v[16:17], v[16:17], v[50:51] op_sel_hi:[1, 0]
	v_pk_mul_f32 v[10:11], v[10:11], v[50:51] op_sel_hi:[1, 0]
	v_pk_mul_f32 v[8:9], v[8:9], v[50:51] op_sel_hi:[1, 0]
	v_pk_mul_f32 v[2:3], v[2:3], v[50:51] op_sel_hi:[1, 0]
	v_pk_mul_f32 v[0:1], v[0:1], v[50:51] op_sel_hi:[1, 0]
	v_pk_mul_f32 v[26:27], v[26:27], v[50:51] op_sel_hi:[1, 0]
	v_pk_mul_f32 v[24:25], v[24:25], v[50:51] op_sel_hi:[1, 0]
	v_pk_mul_f32 v[22:23], v[22:23], v[50:51] op_sel_hi:[1, 0]
	v_pk_mul_f32 v[20:21], v[20:21], v[50:51] op_sel_hi:[1, 0]
	v_pk_mul_f32 v[14:15], v[14:15], v[50:51] op_sel_hi:[1, 0]
	v_pk_mul_f32 v[12:13], v[12:13], v[50:51] op_sel_hi:[1, 0]
	v_pk_mul_f32 v[6:7], v[6:7], v[50:51] op_sel_hi:[1, 0]
	v_pk_mul_f32 v[4:5], v[4:5], v[50:51] op_sel_hi:[1, 0]
	v_pk_mul_f32 v[16:17], v[132:133], v[16:17]
	v_pk_mul_f32 v[18:19], v[134:135], v[18:19]
	v_pk_add_f32 v[28:29], v[138:139], 1.0 op_sel_hi:[1, 0]
	v_pk_add_f32 v[30:31], v[136:137], 1.0 op_sel_hi:[1, 0]
	v_pk_fma_f32 v[18:19], v[28:29], v[18:19], v[142:143]
	v_pk_fma_f32 v[16:17], v[30:31], v[16:17], v[140:141]
	s_nop 0
	v_cvt_pk_bf16_f32 v16, v16, v17
	v_cvt_pk_bf16_f32 v17, v18, v19
	global_store_dwordx2 v[78:79], v[16:17], off offset:512
	s_nop 0
	v_pk_mul_f32 v[8:9], v[150:151], v[8:9]
	v_pk_mul_f32 v[10:11], v[152:153], v[10:11]
	v_pk_add_f32 v[16:17], v[156:157], 1.0 op_sel_hi:[1, 0]
	v_pk_add_f32 v[18:19], v[154:155], 1.0 op_sel_hi:[1, 0]
	v_pk_fma_f32 v[10:11], v[16:17], v[10:11], v[160:161]
	v_pk_fma_f32 v[8:9], v[18:19], v[8:9], v[158:159]
	s_nop 0
	v_cvt_pk_bf16_f32 v8, v8, v9
	v_cvt_pk_bf16_f32 v9, v10, v11
	global_store_dwordx2 v[78:79], v[8:9], off offset:1024
	s_nop 0
	v_pk_mul_f32 v[0:1], v[162:163], v[0:1]
	v_pk_mul_f32 v[2:3], v[164:165], v[2:3]
	v_pk_add_f32 v[8:9], v[176:177], 1.0 op_sel_hi:[1, 0]
	v_pk_add_f32 v[10:11], v[174:175], 1.0 op_sel_hi:[1, 0]
	v_pk_fma_f32 v[2:3], v[8:9], v[2:3], v[180:181]
	v_pk_fma_f32 v[0:1], v[10:11], v[0:1], v[178:179]
	s_nop 0
	v_cvt_pk_bf16_f32 v0, v0, v1
	v_cvt_pk_bf16_f32 v1, v2, v3
	global_store_dwordx2 v[78:79], v[0:1], off offset:1536
	s_nop 0
	v_pk_mul_f32 v[0:1], v[182:183], v[24:25]
	v_pk_mul_f32 v[2:3], v[184:185], v[26:27]
	v_pk_add_f32 v[10:11], v[188:189], 1.0 op_sel_hi:[1, 0]
	v_pk_add_f32 v[8:9], v[186:187], 1.0 op_sel_hi:[1, 0]
	v_pk_fma_f32 v[2:3], v[2:3], v[10:11], v[192:193]
	v_pk_fma_f32 v[0:1], v[0:1], v[8:9], v[190:191]
	s_nop 0
	v_cvt_pk_bf16_f32 v0, v0, v1
	v_cvt_pk_bf16_f32 v1, v2, v3
	global_store_dwordx2 v[78:79], v[0:1], off offset:2048
	s_nop 0
	v_pk_mul_f32 v[0:1], v[20:21], v[194:195]
	v_pk_mul_f32 v[2:3], v[22:23], v[196:197]
	v_pk_add_f32 v[10:11], v[200:201], 1.0 op_sel_hi:[1, 0]
	v_pk_add_f32 v[8:9], v[198:199], 1.0 op_sel_hi:[1, 0]
	v_pk_fma_f32 v[2:3], v[2:3], v[10:11], v[204:205]
	v_pk_fma_f32 v[0:1], v[0:1], v[8:9], v[202:203]
	s_nop 0
	v_cvt_pk_bf16_f32 v0, v0, v1
	v_cvt_pk_bf16_f32 v1, v2, v3
	global_store_dwordx2 v[78:79], v[0:1], off offset:2560
	s_nop 0
	v_pk_mul_f32 v[0:1], v[12:13], v[206:207]
	v_pk_mul_f32 v[2:3], v[14:15], v[208:209]
	v_pk_add_f32 v[10:11], v[212:213], 1.0 op_sel_hi:[1, 0]
	v_pk_add_f32 v[8:9], v[210:211], 1.0 op_sel_hi:[1, 0]
	v_pk_fma_f32 v[2:3], v[2:3], v[10:11], v[216:217]
	v_pk_fma_f32 v[0:1], v[0:1], v[8:9], v[214:215]
	s_nop 0
	v_cvt_pk_bf16_f32 v0, v0, v1
	v_cvt_pk_bf16_f32 v1, v2, v3
	global_store_dwordx2 v[78:79], v[0:1], off offset:3072
	s_nop 0
	v_pk_mul_f32 v[0:1], v[4:5], v[218:219]
	v_pk_mul_f32 v[2:3], v[6:7], v[220:221]
	v_pk_add_f32 v[4:5], v[224:225], 1.0 op_sel_hi:[1, 0]
	v_pk_add_f32 v[6:7], v[222:223], 1.0 op_sel_hi:[1, 0]
	v_pk_fma_f32 v[2:3], v[2:3], v[4:5], v[228:229]
	v_pk_fma_f32 v[0:1], v[0:1], v[6:7], v[226:227]
	s_nop 0
	v_cvt_pk_bf16_f32 v0, v0, v1
	v_cvt_pk_bf16_f32 v1, v2, v3
	global_store_dwordx2 v[78:79], v[0:1], off offset:3584
	s_cbranch_scc0 .LBB0_261

; __device__ __forceinline__ unsigned pk2(float lo, float hi) { f32x2 v = {lo, hi}; bf16x2_t b = __builtin_convertvector(v, bf16x2_t); return __builtin_bit_cast(unsigned, b); }
; __device__ __forceinline__ float siluf_(float x) { return x * sigmoidf_(x); }
; __device__ __forceinline__ void gla3_item(LAS unsigned char* lds, const Params& p, int l, int b, int h, int ci, int tid, int wave, int lane) {
;     ...
;     __syncthreads();
;     const float rstd = 1.f / sqrtf((SSQ[16 * tb + fr] + SSQ[64 + 16 * tb + fr]) * (1.f / 128.f) + 1e-6f);
;     const size_t row = rowbase + 16 * tb + fr;
;     bf16* G = (bf16*)(p.ws + WS_BR);
; #pragma unroll
;     for (int q = 0; q < 4; ++q) { const int dv0 = 16 * (4 * wh + q) + 4 * fq;
;         const f32x4 gn = *(const f32x4*)(p.g_norm + l * 128 + dv0); const u32x2 rr = *(const u32x2*)(P + row * PS + C_GR + h * 128 + dv0);
;         const float o0 = acc[q][0] * rstd * gn[0] * siluf_(bflo(rr.x)), o1 = acc[q][1] * rstd * gn[1] * siluf_(bfhi(rr.x)), o2 = acc[q][2] * rstd * gn[2] * siluf_(bflo(rr.y)), o3 = acc[q][3] * rstd * gn[3] * siluf_(bfhi(rr.y));
;         u32x2 w; w.x = pk2(o0, o1); w.y = pk2(o2, o3); *(u32x2*)(G + row * DM + 512 + h * 128 + dv0) = w; }
.LBB0_658:
	s_or_b64 exec, exec, s[6:7]
	v_lshl_add_u64 v[16:17], s[30:31], 0, v[78:79]
	v_mov_b64_e32 v[18:19], s[10:11]
	v_mad_u64_u32 v[18:19], s[4:5], v16, s90, v[18:19]
	v_mov_b32_e32 v20, v19
	v_mad_u64_u32 v[20:21], s[4:5], v17, s90, v[20:21]
	v_mov_b32_e32 v19, v20
	v_lshl_add_u64 v[18:19], v[18:19], 0, s[22:23]
	s_mov_b64 s[4:5], 0x1800
	v_lshl_add_u64 v[18:19], v[18:19], 0, s[4:5]
	v_lshl_add_u64 v[24:25], v[18:19], 0, v[88:89]
	global_load_dwordx2 v[186:187], v[24:25], off
	global_load_dwordx2 v[188:189], v[24:25], off offset:32
	global_load_dwordx2 v[190:191], v[24:25], off offset:64
	v_lshl_add_u64 v[194:195], v[18:19], 0, v[90:91]
	global_load_dwordx2 v[192:193], v[194:195], off
	global_load_dwordx4 v[196:199], v[80:81], off
	global_load_dwordx4 v[200:203], v[80:81], off offset:64
	global_load_dwordx4 v[204:207], v[80:81], off offset:128
	global_load_dwordx4 v[208:211], v[82:83], off
	s_waitcnt lgkmcnt(0)
	s_barrier
	ds_read2st64_b32 v[28:29], v174 offset1:1
	s_mov_b32 s4, 0xf800000
	v_lshlrev_b64 v[16:17], 12, v[16:17]
	v_lshl_add_u64 v[16:17], s[0:1], 0, v[16:17]
	v_lshl_add_u64 v[16:17], v[16:17], 0, s[22:23]
	s_waitcnt lgkmcnt(0)
	v_add_f32_e32 v28, v28, v29
	v_fmamk_f32 v28, v28, 0x3c000000, v167
	v_mul_f32_e32 v29, 0x4f800000, v28
	v_cmp_gt_f32_e32 vcc, s4, v28
	s_mov_b64 s[4:5], 0x4c00400
	v_lshl_add_u64 v[16:17], v[16:17], 0, s[4:5]
	v_cndmask_b32_e32 v30, v28, v29, vcc
	v_sqrt_f32_e32 v31, v30
	v_lshl_add_u64 v[28:29], v[16:17], 0, v[88:89]
	s_add_i32 s2, s2, s84
	s_cmp_ge_i32 s2, s19
	v_add_u32_e32 v32, -1, v31
	v_add_u32_e32 v33, 1, v31
	v_fma_f32 v36, -v32, v31, v30
	v_fma_f32 v37, -v33, v31, v30
	v_cmp_ge_f32_e64 s[80:81], 0, v36
	s_nop 1
	v_cndmask_b32_e64 v31, v31, v32, s[80:81]
	v_cmp_lt_f32_e64 s[80:81], 0, v37
	s_nop 1
	v_cndmask_b32_e64 v31, v31, v33, s[80:81]
	v_mul_f32_e32 v32, 0x37800000, v31
	v_cndmask_b32_e32 v31, v31, v32, vcc
	v_cmp_class_f32_e32 vcc, v30, v168
	s_nop 1
	v_cndmask_b32_e32 v32, v31, v30, vcc
	v_div_scale_f32 v33, s[4:5], v32, v32, 1.0
	v_rcp_f32_e32 v36, v33
	v_div_scale_f32 v37, vcc, 1.0, v32, 1.0
	s_nop 0
	v_fma_f32 v38, -v33, v36, 1.0
	v_fmac_f32_e32 v36, v38, v36
	v_mul_f32_e32 v38, v37, v36
	v_fma_f32 v39, -v33, v38, v37
	v_fmac_f32_e32 v38, v39, v36
	v_fma_f32 v33, -v33, v38, v37
	v_div_fmas_f32 v33, v33, v36, v38
	v_div_fixup_f32 v32, v33, v32, 1.0
	v_pk_mul_f32 v[0:1], v[0:1], v[32:33] op_sel_hi:[1,0]
	v_pk_mul_f32 v[2:3], v[2:3], v[32:33] op_sel_hi:[1,0]
	s_waitcnt vmcnt(0)
	v_lshlrev_b32_e32 v36, 16, v186
	v_and_b32_e32 v37, 0xffff0000, v186
	v_lshlrev_b32_e32 v26, 16, v187
	v_and_b32_e32 v27, 0xffff0000, v187
	v_mul_f32_e32 v33, 0xbfb8aa3b, v36
	v_mul_f32_e32 v38, 0xbfb8aa3b, v37
	v_mul_f32_e32 v39, 0xbfb8aa3b, v26
	v_mul_f32_e32 v40, 0xbfb8aa3b, v27
	v_exp_f32_e32 v33, v33
	v_exp_f32_e32 v38, v38
	v_exp_f32_e32 v39, v39
	v_exp_f32_e32 v40, v40
	v_add_f32_e32 v33, 1.0, v33
	v_add_f32_e32 v41, 1.0, v38
	v_add_f32_e32 v42, 1.0, v39
	v_add_f32_e32 v43, 1.0, v40
	v_rcp_f32_e32 v38, v33
	v_rcp_f32_e32 v39, v41
	v_rcp_f32_e32 v40, v42
	v_rcp_f32_e32 v41, v43
	v_pk_mul_f32 v[0:1], v[196:197], v[0:1]
	v_pk_mul_f32 v[2:3], v[198:199], v[2:3]
	v_pk_mul_f32 v[20:21], v[38:39], v[36:37]
	v_pk_mul_f32 v[22:23], v[40:41], v[26:27]
	v_pk_mul_f32 v[0:1], v[0:1], v[20:21]
	v_pk_mul_f32 v[2:3], v[2:3], v[22:23]
	v_cvt_pk_bf16_f32 v0, v0, v1
	v_cvt_pk_bf16_f32 v1, v2, v3
	global_store_dwordx2 v[28:29], v[0:1], off
	v_pk_mul_f32 v[4:5], v[4:5], v[32:33] op_sel_hi:[1,0]
	v_pk_mul_f32 v[6:7], v[6:7], v[32:33] op_sel_hi:[1,0]
	v_pk_mul_f32 v[8:9], v[8:9], v[32:33] op_sel_hi:[1,0]
	v_pk_mul_f32 v[10:11], v[10:11], v[32:33] op_sel_hi:[1,0]
	v_lshlrev_b32_e32 v20, 16, v188
	v_and_b32_e32 v21, 0xffff0000, v188
	v_lshlrev_b32_e32 v22, 16, v189
	v_and_b32_e32 v23, 0xffff0000, v189
	v_mul_f32_e32 v26, 0xbfb8aa3b, v20
	v_mul_f32_e32 v27, 0xbfb8aa3b, v21
	v_mul_f32_e32 v30, 0xbfb8aa3b, v22
	v_mul_f32_e32 v31, 0xbfb8aa3b, v23
	v_exp_f32_e32 v26, v26
	v_exp_f32_e32 v27, v27
	v_exp_f32_e32 v30, v30
	v_exp_f32_e32 v31, v31
	v_add_f32_e32 v26, 1.0, v26
	v_add_f32_e32 v27, 1.0, v27
	v_add_f32_e32 v30, 1.0, v30
	v_add_f32_e32 v31, 1.0, v31
	v_rcp_f32_e32 v26, v26
	v_rcp_f32_e32 v27, v27
	v_rcp_f32_e32 v30, v30
	v_rcp_f32_e32 v31, v31
	v_pk_mul_f32 v[20:21], v[26:27], v[20:21]
	v_pk_mul_f32 v[22:23], v[30:31], v[22:23]
	v_pk_mul_f32 v[0:1], v[200:201], v[4:5]
	v_pk_mul_f32 v[2:3], v[202:203], v[6:7]
	v_pk_mul_f32 v[0:1], v[0:1], v[20:21]
	v_pk_mul_f32 v[2:3], v[2:3], v[22:23]
	v_cvt_pk_bf16_f32 v0, v0, v1
	v_cvt_pk_bf16_f32 v1, v2, v3
	global_store_dwordx2 v[28:29], v[0:1], off offset:32
	v_lshlrev_b32_e32 v6, 16, v190
	v_and_b32_e32 v7, 0xffff0000, v190
	v_lshlrev_b32_e32 v18, 16, v191
	v_and_b32_e32 v19, 0xffff0000, v191
	v_mul_f32_e32 v20, 0xbfb8aa3b, v6
	v_mul_f32_e32 v21, 0xbfb8aa3b, v7
	v_mul_f32_e32 v22, 0xbfb8aa3b, v18
	v_mul_f32_e32 v23, 0xbfb8aa3b, v19
	v_exp_f32_e32 v20, v20
	v_exp_f32_e32 v21, v21
	v_exp_f32_e32 v22, v22
	v_exp_f32_e32 v23, v23
	v_add_f32_e32 v20, 1.0, v20
	v_add_f32_e32 v21, 1.0, v21
	v_add_f32_e32 v22, 1.0, v22
	v_add_f32_e32 v23, 1.0, v23
	v_rcp_f32_e32 v20, v20
	v_rcp_f32_e32 v21, v21
	v_rcp_f32_e32 v22, v22
	v_rcp_f32_e32 v23, v23
	v_pk_mul_f32 v[6:7], v[20:21], v[6:7]
	v_pk_mul_f32 v[18:19], v[22:23], v[18:19]
	v_pk_mul_f32 v[0:1], v[8:9], v[204:205]
	v_pk_mul_f32 v[2:3], v[10:11], v[206:207]
	v_pk_mul_f32 v[0:1], v[0:1], v[6:7]
	v_pk_mul_f32 v[2:3], v[2:3], v[18:19]
	v_cvt_pk_bf16_f32 v0, v0, v1
	v_cvt_pk_bf16_f32 v1, v2, v3
	global_store_dwordx2 v[28:29], v[0:1], off offset:64
	s_nop 0
	v_pk_mul_f32 v[8:9], v[12:13], v[32:33] op_sel_hi:[1,0]
	v_lshl_add_u64 v[6:7], v[16:17], 0, v[90:91]
	v_pk_mul_f32 v[10:11], v[14:15], v[32:33] op_sel_hi:[1,0]
	v_lshlrev_b32_e32 v12, 16, v192
	v_and_b32_e32 v13, 0xffff0000, v192
	v_lshlrev_b32_e32 v4, 16, v193
	v_and_b32_e32 v5, 0xffff0000, v193
	v_mul_f32_e32 v14, 0xbfb8aa3b, v12
	v_mul_f32_e32 v15, 0xbfb8aa3b, v13
	v_mul_f32_e32 v16, 0xbfb8aa3b, v4
	v_mul_f32_e32 v17, 0xbfb8aa3b, v5
	v_exp_f32_e32 v14, v14
	v_exp_f32_e32 v15, v15
	v_exp_f32_e32 v16, v16
	v_exp_f32_e32 v17, v17
	v_add_f32_e32 v14, 1.0, v14
	v_add_f32_e32 v15, 1.0, v15
	v_add_f32_e32 v16, 1.0, v16
	v_add_f32_e32 v17, 1.0, v17
	v_rcp_f32_e32 v14, v14
	v_rcp_f32_e32 v15, v15
	v_rcp_f32_e32 v16, v16
	v_rcp_f32_e32 v17, v17
	v_pk_mul_f32 v[0:1], v[8:9], v[208:209]
	v_pk_mul_f32 v[2:3], v[10:11], v[210:211]
	v_pk_mul_f32 v[8:9], v[14:15], v[12:13]
	v_pk_mul_f32 v[4:5], v[16:17], v[4:5]
	v_pk_mul_f32 v[0:1], v[0:1], v[8:9]
	v_pk_mul_f32 v[2:3], v[2:3], v[4:5]
	v_cvt_pk_bf16_f32 v0, v0, v1
	v_cvt_pk_bf16_f32 v1, v2, v3
	global_store_dwordx2 v[6:7], v[0:1], off
	s_cbranch_scc1 .LBB0_685

; __device__ __forceinline__ void norm_rows(const float* srcL, const float* srcC, const float* g, const float* mv, int sc_idx, int sh_idx, bf16* out, int nrows, int gw, int NGW, int lane, const float* part, int nsplit, float* wb) {
;     for (int row = gw; row < nrows; row += NGW) {
;         const bool isc = row >= ML;
;         const f32x4* src = (const f32x4*)(isc ? srcC + (size_t)(row - ML) * DM : srcL + (size_t)row * DM) + lane;
;         const float* mvv = mv + (isc ? 2 : (row >> 13)) * ADA;
;         f32x4 v[8]; float s = 0.f;
; #pragma unroll
;         for (int j = 0; j < 8; ++j) v[j] = src[64 * j];
;         if (isc && nsplit > 0) {
;             const f32x4* pp = (const f32x4*)(part + (size_t)(row - ML) * DM) + lane;
; #pragma unroll 4
;             for (int sp = 0; sp < nsplit; ++sp) {
; #pragma unroll
;                 for (int j = 0; j < 8; ++j) v[j] += pp[(size_t)sp * (MC * DM / 4) + 64 * j];
;             }
;             if (wb) { f32x4* w4 = (f32x4*)(wb + (size_t)(row - ML) * DM) + lane;
; #pragma unroll
;                 for (int j = 0; j < 8; ++j) w4[64 * j] = v[j]; }
;         }
; #pragma unroll
;         for (int j = 0; j < 8; ++j) s += (v[j].x * v[j].x + v[j].y * v[j].y) + (v[j].z * v[j].z + v[j].w * v[j].w);
;         const float rstd = 1.f / sqrtf(wave_sum(s) * (1.f / DM) + 1e-6f);
.LBB0_951:
	s_min_i32 s4, s0, 0x4000
	s_ashr_i32 s4, s4, 13
	s_mulk_i32 s4, 0x3000
	s_ashr_i32 s5, s4, 31
	s_lshl_b64 s[4:5], s[4:5], 2
	s_add_u32 s10, s6, s4
	s_addc_u32 s11, s7, s5
	s_add_u32 s8, s10, 0x8000
	s_addc_u32 s9, s11, 0
	s_add_u32 s10, s10, 0x6000
	s_addc_u32 s11, s11, 0
	global_load_dwordx4 v[100:103], v[38:39], off
	global_load_dwordx4 v[104:107], v62, s[8:9]
	global_load_dwordx4 v[108:111], v62, s[10:11]
	global_load_dwordx4 v[112:115], v[38:39], off offset:1024
	global_load_dwordx4 v[116:119], v63, s[8:9]
	global_load_dwordx4 v[120:123], v63, s[10:11]
	global_load_dwordx4 v[124:127], v[38:39], off offset:2048
	global_load_dwordx4 v[128:131], v64, s[8:9]
	global_load_dwordx4 v[132:135], v64, s[10:11]
	global_load_dwordx4 v[136:139], v[38:39], off offset:3072
	global_load_dwordx4 v[140:143], v65, s[8:9]
	global_load_dwordx4 v[150:153], v65, s[10:11]
	global_load_dwordx4 v[154:157], v[40:41], off
	global_load_dwordx4 v[158:161], v66, s[8:9]
	global_load_dwordx4 v[162:165], v66, s[10:11]
	global_load_dwordx4 v[174:177], v[42:43], off
	global_load_dwordx4 v[178:181], v67, s[8:9]
	global_load_dwordx4 v[182:185], v67, s[10:11]
	global_load_dwordx4 v[186:189], v[44:45], off
	global_load_dwordx4 v[190:193], v68, s[8:9]
	global_load_dwordx4 v[194:197], v68, s[10:11]
	global_load_dwordx4 v[198:201], v[46:47], off
	global_load_dwordx4 v[202:205], v69, s[8:9]
	global_load_dwordx4 v[206:209], v69, s[10:11]
	s_waitcnt vmcnt(31)
	v_pk_mul_f32 v[76:77], v[24:25], v[24:25]
	s_waitcnt vmcnt(30)
	v_pk_mul_f32 v[78:79], v[20:21], v[20:21]
	v_pk_mul_f32 v[72:73], v[26:27], v[26:27]
	v_pk_mul_f32 v[74:75], v[22:23], v[22:23]
	v_mov_b32_e32 v80, v76
	v_mov_b32_e32 v81, v78
	v_mov_b32_e32 v78, v77
	s_waitcnt vmcnt(29)
	v_pk_mul_f32 v[54:55], v[18:19], v[18:19]
	v_pk_mul_f32 v[70:71], v[16:17], v[16:17]
	v_pk_add_f32 v[76:77], v[80:81], v[78:79]
	v_mov_b32_e32 v78, v72
	v_mov_b32_e32 v79, v74
	v_mov_b32_e32 v74, v73
	v_pk_add_f32 v[72:73], v[78:79], v[74:75]
	v_pk_mov_b32 v[74:75], v[70:71], v[54:55] op_sel:[1,0]
	v_mov_b32_e32 v71, v55
	v_pk_add_f32 v[54:55], v[74:75], v[70:71]
	v_pk_add_f32 v[72:73], v[76:77], v[72:73]
	v_pk_add_f32 v[54:55], v[54:55], v[54:55] op_sel_hi:[0,1]
	s_waitcnt vmcnt(28)
	v_mul_f32_e32 v54, v12, v12
	v_pk_fma_f32 v[70:71], v[12:13], v[12:13], v[54:55] op_sel_hi:[1,1,0]
	v_mul_f32_e32 v54, v14, v14
	v_pk_add_f32 v[72:73], v[72:73], v[72:73] op_sel_hi:[0,1]
	v_pk_fma_f32 v[74:75], v[14:15], v[14:15], v[54:55] op_sel_hi:[1,1,0]
	s_waitcnt vmcnt(27)
	v_mul_f32_e32 v70, v8, v8
	v_mul_f32_e32 v74, v9, v9
	v_mul_f32_e32 v54, v10, v10
	v_mul_f32_e32 v72, v11, v11
	s_waitcnt vmcnt(26)
	v_pk_mul_f32 v[50:51], v[6:7], v[6:7]
	v_pk_mul_f32 v[52:53], v[4:5], v[4:5]
	v_pk_add_f32 v[70:71], v[70:71], v[74:75]
	v_pk_add_f32 v[54:55], v[54:55], v[72:73]
	v_pk_add_f32 v[54:55], v[70:71], v[54:55]
	v_pk_mov_b32 v[70:71], v[52:53], v[50:51] op_sel:[1,0]
	v_mov_b32_e32 v53, v51
	v_pk_add_f32 v[50:51], v[70:71], v[52:53]
	v_pk_add_f32 v[54:55], v[54:55], v[54:55] op_sel_hi:[0,1]
	v_pk_add_f32 v[50:51], v[50:51], v[50:51] op_sel_hi:[0,1]
	s_waitcnt vmcnt(25)
	v_mul_f32_e32 v50, v0, v0
	v_pk_fma_f32 v[52:53], v[0:1], v[0:1], v[50:51] op_sel_hi:[1,1,0]
	v_mul_f32_e32 v50, v2, v2
	v_pk_fma_f32 v[70:71], v[2:3], v[2:3], v[50:51] op_sel_hi:[1,1,0]
	s_waitcnt vmcnt(24)
	v_mul_f32_e32 v52, v28, v28
	v_mul_f32_e32 v70, v29, v29
	v_mul_f32_e32 v50, v30, v30
	v_mul_f32_e32 v54, v31, v31
	v_pk_add_f32 v[52:53], v[52:53], v[70:71]
	v_pk_add_f32 v[50:51], v[50:51], v[54:55]
	v_pk_add_f32 v[50:51], v[52:53], v[50:51]
	v_add_f32_e32 v50, v50, v51
	ds_bpermute_b32 v51, v56, v50
	s_waitcnt lgkmcnt(0)
	v_add_f32_e32 v50, v50, v51
	ds_bpermute_b32 v51, v57, v50
	s_waitcnt lgkmcnt(0)
	v_add_f32_e32 v50, v50, v51
	ds_bpermute_b32 v51, v58, v50
	s_add_u32 s0, s0, s88
	s_addc_u32 s1, s1, s89
	s_cmp_lt_i32 s0, s2
	s_waitcnt lgkmcnt(0)
	v_add_f32_e32 v50, v50, v51
	ds_bpermute_b32 v51, v59, v50
	s_waitcnt lgkmcnt(0)
	v_add_f32_e32 v50, v50, v51
	ds_bpermute_b32 v51, v60, v50
	s_waitcnt lgkmcnt(0)
	v_add_f32_e32 v50, v50, v51
	ds_bpermute_b32 v51, v61, v50
	s_waitcnt lgkmcnt(0)
; __device__ __forceinline__ unsigned pk2(float lo, float hi) { f32x2 v = {lo, hi}; bf16x2_t b = __builtin_convertvector(v, bf16x2_t); return __builtin_bit_cast(unsigned, b); }
; __device__ __forceinline__ void norm_rows(const float* srcL, const float* srcC, const float* g, const float* mv, int sc_idx, int sh_idx, bf16* out, int nrows, int gw, int NGW, int lane, const float* part, int nsplit, float* wb) {
;     ...
;         const float rstd = 1.f / sqrtf(wave_sum(s) * (1.f / DM) + 1e-6f);
;         u32x2* o = (u32x2*)(out + (size_t)row * DM) + lane;
; #pragma unroll
;         for (int j = 0; j < 8; ++j) {
;             const int col = 4 * (lane + 64 * j);
;             const f32x4 gg = *(const f32x4*)(g + col), sc = *(const f32x4*)(mvv + sc_idx * DM + col), sh = *(const f32x4*)(mvv + sh_idx * DM + col);
;             const f32x4 y = (v[j] * rstd) * gg * (sc + 1.f) + sh;
;             u32x2 w; w.x = pk2(y.x, y.y); w.y = pk2(y.z, y.w); o[64 * j] = w;
;         }
	v_add_f32_e32 v50, v50, v51
	v_fmamk_f32 v50, v50, 0x3a000000, v167
	v_cmp_gt_f32_e32 vcc, s72, v50
	v_mul_f32_e32 v51, 0x4f800000, v50
	s_nop 0
	v_cndmask_b32_e32 v50, v50, v51, vcc
	v_sqrt_f32_e32 v51, v50
	s_nop 0
	v_add_u32_e32 v52, -1, v51
	v_fma_f32 v53, -v52, v51, v50
	v_cmp_ge_f32_e64 s[38:39], 0, v53
	v_add_u32_e32 v53, 1, v51
	s_nop 0
	v_cndmask_b32_e64 v52, v51, v52, s[38:39]
	v_fma_f32 v51, -v53, v51, v50
	v_cmp_lt_f32_e64 s[38:39], 0, v51
	s_nop 1
	v_cndmask_b32_e64 v51, v52, v53, s[38:39]
	v_mul_f32_e32 v52, 0x37800000, v51
	v_cndmask_b32_e32 v51, v51, v52, vcc
	v_cmp_class_f32_e32 vcc, v50, v168
	s_nop 1
	v_cndmask_b32_e32 v50, v51, v50, vcc
	v_div_scale_f32 v51, s[4:5], v50, v50, 1.0
	v_rcp_f32_e32 v52, v51
	v_readlane_b32 s4, v243, 61
	v_readlane_b32 s5, v243, 62
	v_fma_f32 v53, -v51, v52, 1.0
	v_fmac_f32_e32 v52, v53, v52
	v_div_scale_f32 v53, vcc, 1.0, v50, 1.0
	v_mul_f32_e32 v54, v53, v52
	v_fma_f32 v55, -v51, v54, v53
	v_fmac_f32_e32 v54, v55, v52
	v_fma_f32 v51, -v51, v54, v53
	v_div_fmas_f32 v51, v51, v52, v54
	v_div_fixup_f32 v50, v51, v50, 1.0
	v_pk_mul_f32 v[26:27], v[26:27], v[50:51] op_sel_hi:[1, 0]
	v_pk_mul_f32 v[24:25], v[24:25], v[50:51] op_sel_hi:[1, 0]
	v_pk_mul_f32 v[22:23], v[22:23], v[50:51] op_sel_hi:[1, 0]
	v_pk_mul_f32 v[20:21], v[20:21], v[50:51] op_sel_hi:[1, 0]
	v_pk_mul_f32 v[18:19], v[18:19], v[50:51] op_sel_hi:[1, 0]
	v_pk_mul_f32 v[16:17], v[16:17], v[50:51] op_sel_hi:[1, 0]
	v_pk_mul_f32 v[14:15], v[14:15], v[50:51] op_sel_hi:[1, 0]
	v_pk_mul_f32 v[12:13], v[12:13], v[50:51] op_sel_hi:[1, 0]
	v_pk_mul_f32 v[10:11], v[10:11], v[50:51] op_sel_hi:[1, 0]
	v_pk_mul_f32 v[8:9], v[8:9], v[50:51] op_sel_hi:[1, 0]
	v_pk_mul_f32 v[6:7], v[6:7], v[50:51] op_sel_hi:[1, 0]
	v_pk_mul_f32 v[4:5], v[4:5], v[50:51] op_sel_hi:[1, 0]
	v_pk_mul_f32 v[2:3], v[2:3], v[50:51] op_sel_hi:[1, 0]
	v_pk_mul_f32 v[0:1], v[0:1], v[50:51] op_sel_hi:[1, 0]
	s_waitcnt vmcnt(0)
	v_pk_mul_f32 v[24:25], v[100:101], v[24:25]
	v_pk_mul_f32 v[26:27], v[102:103], v[26:27]
	v_pk_add_f32 v[52:53], v[106:107], 1.0 op_sel_hi:[1, 0]
	v_pk_add_f32 v[54:55], v[104:105], 1.0 op_sel_hi:[1, 0]
	v_pk_fma_f32 v[26:27], v[52:53], v[26:27], v[110:111]
	v_pk_fma_f32 v[24:25], v[54:55], v[24:25], v[108:109]
	s_nop 0
	v_cvt_pk_bf16_f32 v24, v24, v25
	v_cvt_pk_bf16_f32 v25, v26, v27
	global_store_dwordx2 v[48:49], v[24:25], off offset:-2048
	s_nop 0
	v_pk_mul_f32 v[20:21], v[112:113], v[20:21]
	v_pk_mul_f32 v[22:23], v[114:115], v[22:23]
	v_pk_add_f32 v[24:25], v[118:119], 1.0 op_sel_hi:[1, 0]
	v_pk_add_f32 v[26:27], v[116:117], 1.0 op_sel_hi:[1, 0]
	v_pk_fma_f32 v[22:23], v[24:25], v[22:23], v[122:123]
	v_pk_fma_f32 v[20:21], v[26:27], v[20:21], v[120:121]
	s_nop 0
	v_cvt_pk_bf16_f32 v20, v20, v21
	v_cvt_pk_bf16_f32 v21, v22, v23
	global_store_dwordx2 v[48:49], v[20:21], off offset:-1536
	s_nop 0
	v_pk_mul_f32 v[16:17], v[124:125], v[16:17]
	v_pk_mul_f32 v[18:19], v[126:127], v[18:19]
	v_pk_add_f32 v[20:21], v[130:131], 1.0 op_sel_hi:[1, 0]
	v_pk_add_f32 v[22:23], v[128:129], 1.0 op_sel_hi:[1, 0]
	v_pk_fma_f32 v[18:19], v[20:21], v[18:19], v[134:135]
	v_pk_fma_f32 v[16:17], v[22:23], v[16:17], v[132:133]
	s_nop 0
	v_cvt_pk_bf16_f32 v16, v16, v17
	v_cvt_pk_bf16_f32 v17, v18, v19
	global_store_dwordx2 v[48:49], v[16:17], off offset:-1024
	s_nop 0
	v_pk_mul_f32 v[12:13], v[136:137], v[12:13]
	v_pk_mul_f32 v[14:15], v[138:139], v[14:15]
	v_pk_add_f32 v[16:17], v[142:143], 1.0 op_sel_hi:[1, 0]
	v_pk_add_f32 v[18:19], v[140:141], 1.0 op_sel_hi:[1, 0]
	v_pk_fma_f32 v[14:15], v[16:17], v[14:15], v[152:153]
	v_pk_fma_f32 v[12:13], v[18:19], v[12:13], v[150:151]
	s_nop 0
	v_cvt_pk_bf16_f32 v12, v12, v13
	v_cvt_pk_bf16_f32 v13, v14, v15
	global_store_dwordx2 v[48:49], v[12:13], off offset:-512
	s_nop 0
	v_pk_mul_f32 v[8:9], v[154:155], v[8:9]
	v_pk_mul_f32 v[10:11], v[156:157], v[10:11]
	v_pk_add_f32 v[12:13], v[160:161], 1.0 op_sel_hi:[1, 0]
	v_pk_add_f32 v[14:15], v[158:159], 1.0 op_sel_hi:[1, 0]
	v_pk_fma_f32 v[10:11], v[10:11], v[12:13], v[164:165]
	v_pk_fma_f32 v[8:9], v[8:9], v[14:15], v[162:163]
	s_nop 0
	v_cvt_pk_bf16_f32 v8, v8, v9
	v_cvt_pk_bf16_f32 v9, v10, v11
	global_store_dwordx2 v[48:49], v[8:9], off
	s_nop 0
	v_pk_mul_f32 v[4:5], v[4:5], v[174:175]
	v_pk_mul_f32 v[6:7], v[6:7], v[176:177]
	v_pk_add_f32 v[8:9], v[180:181], 1.0 op_sel_hi:[1, 0]
	v_pk_add_f32 v[10:11], v[178:179], 1.0 op_sel_hi:[1, 0]
	v_pk_fma_f32 v[6:7], v[6:7], v[8:9], v[184:185]
	v_pk_fma_f32 v[4:5], v[4:5], v[10:11], v[182:183]
	s_nop 0
	v_cvt_pk_bf16_f32 v4, v4, v5
	v_cvt_pk_bf16_f32 v5, v6, v7
	global_store_dwordx2 v[48:49], v[4:5], off offset:512
	s_nop 0
	v_pk_mul_f32 v[0:1], v[0:1], v[186:187]
	v_pk_mul_f32 v[2:3], v[2:3], v[188:189]
	v_pk_add_f32 v[4:5], v[192:193], 1.0 op_sel_hi:[1, 0]
	v_pk_add_f32 v[6:7], v[190:191], 1.0 op_sel_hi:[1, 0]
	v_pk_fma_f32 v[2:3], v[2:3], v[4:5], v[196:197]
	v_pk_fma_f32 v[0:1], v[0:1], v[6:7], v[194:195]
	v_pk_mul_f32 v[12:13], v[30:31], v[50:51] op_sel_hi:[1, 0]
	v_cvt_pk_bf16_f32 v0, v0, v1
	v_cvt_pk_bf16_f32 v1, v2, v3
	global_store_dwordx2 v[48:49], v[0:1], off offset:1024
	s_nop 0
	v_pk_mul_f32 v[14:15], v[28:29], v[50:51] op_sel_hi:[1, 0]
	v_pk_mul_f32 v[2:3], v[12:13], v[200:201]
	v_pk_mul_f32 v[0:1], v[14:15], v[198:199]
	v_pk_add_f32 v[6:7], v[204:205], 1.0 op_sel_hi:[1, 0]
	v_pk_add_f32 v[4:5], v[202:203], 1.0 op_sel_hi:[1, 0]
	v_pk_fma_f32 v[2:3], v[2:3], v[6:7], v[208:209]
	v_pk_fma_f32 v[0:1], v[0:1], v[4:5], v[206:207]
	s_nop 0
	v_cvt_pk_bf16_f32 v0, v0, v1
	v_cvt_pk_bf16_f32 v1, v2, v3
	global_store_dwordx2 v[48:49], v[0:1], off offset:1536
	v_lshl_add_u64 v[48:49], v[48:49], 0, s[4:5]
	s_cbranch_scc0 .LBB0_954

; __device__ __forceinline__ void final_norm(float* h, const float* g, int gw, int NGW, int lane) {
;     for (int row = gw; row < ML; row += NGW) {
;         f32x4* src = (f32x4*)(h + (size_t)row * DM) + lane;
;         f32x4 v[8]; float s = 0.f;
; #pragma unroll
;         for (int j = 0; j < 8; ++j) { v[j] = src[64 * j]; s += (v[j].x * v[j].x + v[j].y * v[j].y) + (v[j].z * v[j].z + v[j].w * v[j].w); }
;         const float rstd = 1.f / sqrtf(wave_sum(s) * (1.f / DM) + 1e-6f);
; #pragma unroll
;         for (int j = 0; j < 8; ++j) { const f32x4 gg = *(const f32x4*)(g + 4 * (lane + 64 * j)); __builtin_nontemporal_store((v[j] * rstd) * gg, src + 64 * j); }
.LBB0_1181:
	v_readlane_b32 s2, v244, 52
	v_readlane_b32 s3, v244, 53
	v_readlane_b32 s9, v243, 46
	v_readfirstlane_b32 s0, v166
	s_ashr_i32 s0, s0, 6
	s_add_i32 s8, s0, s9
	s_cmpk_gt_i32 s8, 0x3fff
	s_cbranch_scc1 .LBB0_1184
	v_and_b32_e32 v1, 64, v172
	v_add_u32_e32 v1, 64, v1
	v_xor_b32_e32 v2, 1, v172
	v_cmp_lt_i32_e32 vcc, v2, v1
	s_load_dwordx4 s[4:7], s[2:3], 0xb8
	v_and_b32_e32 v0, 63, v166
	v_cndmask_b32_e32 v2, v172, v2, vcc
	v_lshlrev_b32_e32 v24, 2, v2
	v_xor_b32_e32 v2, 2, v172
	v_cmp_lt_i32_e32 vcc, v2, v1
	v_lshlrev_b32_e32 v0, 4, v0
	s_ashr_i32 s1, s0, 31
	v_cndmask_b32_e32 v2, v172, v2, vcc
	v_lshlrev_b32_e32 v25, 2, v2
	v_xor_b32_e32 v2, 4, v172
	v_cmp_lt_i32_e32 vcc, v2, v1
	s_add_u32 s0, s0, s9
	s_mov_b64 s[2:3], 0x1000
	v_cndmask_b32_e32 v2, v172, v2, vcc
	v_lshlrev_b32_e32 v26, 2, v2
	v_xor_b32_e32 v2, 8, v172
	v_cmp_lt_i32_e32 vcc, v2, v1
	v_mov_b32_e32 v30, 0x358637bd
	v_mov_b32_e32 v31, 0x260
	v_cndmask_b32_e32 v2, v172, v2, vcc
	v_lshlrev_b32_e32 v27, 2, v2
	v_xor_b32_e32 v2, 16, v172
	v_cmp_lt_i32_e32 vcc, v2, v1
	s_nop 1
	v_cndmask_b32_e32 v2, v172, v2, vcc
	v_lshlrev_b32_e32 v28, 2, v2
	v_xor_b32_e32 v2, 32, v172
	v_cmp_lt_i32_e32 vcc, v2, v1
	s_nop 1
	v_cndmask_b32_e32 v1, v172, v2, vcc
	v_lshlrev_b32_e32 v29, 2, v1
	v_mov_b32_e32 v1, 0
	s_waitcnt lgkmcnt(0)
	v_lshl_add_u64 v[12:13], s[4:5], 0, v[0:1]
	s_mov_b64 s[4:5], 0x1400
	v_lshl_add_u64 v[16:17], v[12:13], 0, s[4:5]
	s_mov_b64 s[4:5], 0x1800
	v_lshl_add_u64 v[18:19], v[12:13], 0, s[4:5]
	s_mov_b64 s[4:5], 0x1c00
	v_lshl_add_u64 v[20:21], v[12:13], 0, s[4:5]
	v_readlane_b32 s4, v243, 47
	s_addc_u32 s1, s1, s4
	s_lshl_b64 s[0:1], s[0:1], 13
	s_add_u32 s0, s6, s0
	s_addc_u32 s1, s7, s1
	v_lshl_add_u64 v[0:1], s[0:1], 0, v[0:1]
	v_lshl_add_u64 v[14:15], v[12:13], 0, s[2:3]
	v_lshl_add_u64 v[22:23], v[0:1], 0, s[2:3]
	s_lshl_b64 s[2:3], s[88:89], 13
	s_mov_b32 s4, 0xf800000
	global_load_dwordx4 v[90:93], v[12:13], off
	global_load_dwordx4 v[94:97], v[12:13], off offset:1024
	global_load_dwordx4 v[98:101], v[12:13], off offset:2048
	global_load_dwordx4 v[102:105], v[12:13], off offset:3072
	global_load_dwordx4 v[106:109], v[14:15], off
	global_load_dwordx4 v[110:113], v[16:17], off
	global_load_dwordx4 v[114:117], v[18:19], off
	global_load_dwordx4 v[118:121], v[20:21], off
	s_waitcnt vmcnt(0)
; __device__ __forceinline__ void final_norm(float* h, const float* g, int gw, int NGW, int lane) {
;     for (int row = gw; row < ML; row += NGW) {
;         f32x4* src = (f32x4*)(h + (size_t)row * DM) + lane;
;         f32x4 v[8]; float s = 0.f;
; #pragma unroll
;         for (int j = 0; j < 8; ++j) { v[j] = src[64 * j]; s += (v[j].x * v[j].x + v[j].y * v[j].y) + (v[j].z * v[j].z + v[j].w * v[j].w); }
;         const float rstd = 1.f / sqrtf(wave_sum(s) * (1.f / DM) + 1e-6f);
; #pragma unroll
;         for (int j = 0; j < 8; ++j) { const f32x4 gg = *(const f32x4*)(g + 4 * (lane + 64 * j)); __builtin_nontemporal_store((v[j] * rstd) * gg, src + 64 * j); }
;     }
.LBB0_1183:
	global_load_dwordx4 v[32:35], v[22:23], off offset:-4096
	global_load_dwordx4 v[8:11], v[22:23], off offset:-3072
	global_load_dwordx4 v[36:39], v[22:23], off offset:-2048
	global_load_dwordx4 v[4:7], v[22:23], off
	global_load_dwordx4 v[40:43], v[22:23], off offset:-1024
	global_load_dwordx4 v[44:47], v[22:23], off offset:1024
	global_load_dwordx4 v[0:3], v[22:23], off offset:3072
	global_load_dwordx4 v[48:51], v[22:23], off offset:2048
	s_add_i32 s8, s8, s88
	s_cmpk_lt_i32 s8, 0x4000
	s_waitcnt vmcnt(7)
	v_mov_b32_e32 v58, v33
	s_waitcnt vmcnt(6)
	v_mov_b32_e32 v59, v9
	v_mov_b32_e32 v62, v35
	v_mov_b32_e32 v63, v11
	v_mov_b32_e32 v56, v32
	v_mov_b32_e32 v57, v8
	v_mov_b32_e32 v60, v34
	v_mov_b32_e32 v61, v10
	s_waitcnt vmcnt(5)
	v_pk_mul_f32 v[64:65], v[38:39], v[38:39]
	v_pk_mul_f32 v[66:67], v[36:37], v[36:37]
	v_pk_mul_f32 v[58:59], v[58:59], v[58:59]
	v_pk_mul_f32 v[62:63], v[62:63], v[62:63]
	v_pk_mov_b32 v[80:81], v[66:67], v[64:65] op_sel:[1,0]
	v_mov_b32_e32 v67, v65
	v_pk_fma_f32 v[56:57], v[56:57], v[56:57], v[58:59]
	v_pk_fma_f32 v[58:59], v[60:61], v[60:61], v[62:63]
	s_waitcnt vmcnt(3)
	v_mul_f32_e32 v68, v41, v41
	v_mul_f32_e32 v70, v43, v43
	v_pk_add_f32 v[60:61], v[80:81], v[66:67]
	v_pk_add_f32 v[56:57], v[56:57], v[58:59]
	v_mul_f32_e32 v79, v4, v4
	v_mul_f32_e32 v82, v5, v5
	v_mul_f32_e32 v83, v6, v6
	v_mul_f32_e32 v84, v7, v7
	v_pk_fma_f32 v[64:65], v[40:41], v[40:41], v[68:69] op_sel_hi:[1,1,0]
	v_pk_fma_f32 v[68:69], v[42:43], v[42:43], v[70:71] op_sel_hi:[1,1,0]
	v_pk_add_f32 v[58:59], v[60:61], v[60:61] op_sel:[0,1] op_sel_hi:[1,0]
	v_pk_add_f32 v[56:57], v[56:57], v[56:57] op_sel:[0,1] op_sel_hi:[1,0]
	s_waitcnt vmcnt(2)
	v_pk_mul_f32 v[72:73], v[46:47], v[46:47]
	v_pk_mul_f32 v[74:75], v[44:45], v[44:45]
	v_mov_b32_e32 v65, v83
	v_mov_b32_e32 v69, v84
	v_mov_b32_e32 v59, v82
	v_mov_b32_e32 v57, v79
	v_pk_mov_b32 v[70:71], v[74:75], v[72:73] op_sel:[1,0]
	v_mov_b32_e32 v75, v73
	v_pk_add_f32 v[60:61], v[64:65], v[68:69]
	v_pk_add_f32 v[56:57], v[56:57], v[58:59]
	s_waitcnt vmcnt(0)
	v_mul_f32_e32 v76, v49, v49
	v_mul_f32_e32 v78, v51, v51
	v_pk_add_f32 v[62:63], v[70:71], v[74:75]
	v_pk_add_f32 v[56:57], v[56:57], v[60:61]
	v_mul_f32_e32 v85, v0, v0
	v_mul_f32_e32 v86, v1, v1
	v_mul_f32_e32 v87, v2, v2
	v_mul_f32_e32 v88, v3, v3
	v_pk_fma_f32 v[72:73], v[48:49], v[48:49], v[76:77] op_sel_hi:[1,1,0]
	v_pk_fma_f32 v[76:77], v[50:51], v[50:51], v[78:79] op_sel_hi:[1,1,0]
	v_pk_add_f32 v[62:63], v[62:63], v[62:63] op_sel:[0,1] op_sel_hi:[1,0]
	v_pk_add_f32 v[56:57], v[56:57], v[56:57] op_sel:[0,1] op_sel_hi:[1,0]
	v_mov_b32_e32 v73, v87
	v_mov_b32_e32 v77, v88
	v_mov_b32_e32 v63, v86
	v_mov_b32_e32 v57, v85
	v_pk_add_f32 v[64:65], v[72:73], v[76:77]
	v_pk_add_f32 v[56:57], v[56:57], v[62:63]
	s_nop 0
	v_pk_add_f32 v[56:57], v[56:57], v[64:65]
	s_nop 0
	v_add_f32_e32 v56, v56, v57
	ds_bpermute_b32 v57, v24, v56
	s_waitcnt lgkmcnt(0)
	v_add_f32_e32 v56, v56, v57
	ds_bpermute_b32 v57, v25, v56
	s_waitcnt lgkmcnt(0)
	v_add_f32_e32 v56, v56, v57
	ds_bpermute_b32 v57, v26, v56
	s_waitcnt lgkmcnt(0)
	v_add_f32_e32 v56, v56, v57
	ds_bpermute_b32 v57, v27, v56
	s_waitcnt lgkmcnt(0)
	v_add_f32_e32 v56, v56, v57
	ds_bpermute_b32 v57, v28, v56
	s_waitcnt lgkmcnt(0)
	v_add_f32_e32 v56, v56, v57
	ds_bpermute_b32 v57, v29, v56
	s_waitcnt lgkmcnt(0)
	v_add_f32_e32 v56, v56, v57
	v_fmamk_f32 v56, v56, 0x3a000000, v30
	v_mul_f32_e32 v57, 0x4f800000, v56
	v_cmp_gt_f32_e32 vcc, s4, v56
	s_nop 1
	v_cndmask_b32_e32 v56, v56, v57, vcc
	v_sqrt_f32_e32 v57, v56
	s_nop 0
	v_add_u32_e32 v58, -1, v57
	v_add_u32_e32 v59, 1, v57
	v_fma_f32 v60, -v58, v57, v56
	v_fma_f32 v61, -v59, v57, v56
	v_cmp_ge_f32_e64 s[0:1], 0, v60
	s_nop 1
	v_cndmask_b32_e64 v57, v57, v58, s[0:1]
	v_cmp_lt_f32_e64 s[0:1], 0, v61
	s_nop 1
	v_cndmask_b32_e64 v57, v57, v59, s[0:1]
	v_mul_f32_e32 v58, 0x37800000, v57
	v_cndmask_b32_e32 v57, v57, v58, vcc
	v_cmp_class_f32_e32 vcc, v56, v31
	s_nop 1
	v_cndmask_b32_e32 v56, v57, v56, vcc
	v_div_scale_f32 v57, s[0:1], v56, v56, 1.0
	v_rcp_f32_e32 v58, v57
	v_div_scale_f32 v59, vcc, 1.0, v56, 1.0
	v_fma_f32 v60, -v57, v58, 1.0
	v_fmac_f32_e32 v58, v60, v58
	v_mul_f32_e32 v60, v59, v58
	v_fma_f32 v61, -v57, v60, v59
	v_fmac_f32_e32 v60, v61, v58
	v_fma_f32 v57, -v57, v60, v59
	v_div_fmas_f32 v57, v57, v58, v60
	v_div_fixup_f32 v56, v57, v56, 1.0
	v_pk_mul_f32 v[32:33], v[32:33], v[56:57] op_sel_hi:[1,0]
	v_pk_mul_f32 v[34:35], v[34:35], v[56:57] op_sel_hi:[1,0]
	v_pk_mul_f32 v[32:33], v[90:91], v[32:33]
	v_pk_mul_f32 v[34:35], v[92:93], v[34:35]
	global_store_dwordx4 v[22:23], v[32:35], off offset:-4096 nt
	v_pk_mul_f32 v[10:11], v[10:11], v[56:57] op_sel_hi:[1,0]
	v_pk_mul_f32 v[8:9], v[8:9], v[56:57] op_sel_hi:[1,0]
	v_pk_mul_f32 v[6:7], v[6:7], v[56:57] op_sel_hi:[1,0]
	v_pk_mul_f32 v[4:5], v[4:5], v[56:57] op_sel_hi:[1,0]
	v_pk_mul_f32 v[2:3], v[2:3], v[56:57] op_sel_hi:[1,0]
	v_pk_mul_f32 v[0:1], v[0:1], v[56:57] op_sel_hi:[1,0]
	v_pk_mul_f32 v[8:9], v[94:95], v[8:9]
	v_pk_mul_f32 v[10:11], v[96:97], v[10:11]
	global_store_dwordx4 v[22:23], v[8:11], off offset:-3072 nt
	v_pk_mul_f32 v[32:33], v[38:39], v[56:57] op_sel_hi:[1,0]
	v_pk_mul_f32 v[34:35], v[36:37], v[56:57] op_sel_hi:[1,0]
	v_pk_mul_f32 v[10:11], v[100:101], v[32:33]
	v_pk_mul_f32 v[8:9], v[98:99], v[34:35]
	global_store_dwordx4 v[22:23], v[8:11], off offset:-2048 nt
	v_pk_mul_f32 v[32:33], v[42:43], v[56:57] op_sel_hi:[1,0]
	v_pk_mul_f32 v[34:35], v[40:41], v[56:57] op_sel_hi:[1,0]
	v_pk_mul_f32 v[10:11], v[104:105], v[32:33]
	v_pk_mul_f32 v[8:9], v[102:103], v[34:35]
	global_store_dwordx4 v[22:23], v[8:11], off offset:-1024 nt
	v_pk_mul_f32 v[4:5], v[106:107], v[4:5]
	v_pk_mul_f32 v[6:7], v[108:109], v[6:7]
	global_store_dwordx4 v[22:23], v[4:7], off nt
	v_pk_mul_f32 v[8:9], v[46:47], v[56:57] op_sel_hi:[1,0]
	v_pk_mul_f32 v[10:11], v[44:45], v[56:57] op_sel_hi:[1,0]
	v_pk_mul_f32 v[6:7], v[112:113], v[8:9]
	v_pk_mul_f32 v[4:5], v[110:111], v[10:11]
	global_store_dwordx4 v[22:23], v[4:7], off offset:1024 nt
	v_pk_mul_f32 v[8:9], v[50:51], v[56:57] op_sel_hi:[1,0]
	v_pk_mul_f32 v[10:11], v[48:49], v[56:57] op_sel_hi:[1,0]
	v_pk_mul_f32 v[6:7], v[8:9], v[116:117]
	v_pk_mul_f32 v[4:5], v[10:11], v[114:115]
	global_store_dwordx4 v[22:23], v[4:7], off offset:2048 nt
	v_pk_mul_f32 v[0:1], v[0:1], v[118:119]
	v_pk_mul_f32 v[2:3], v[2:3], v[120:121]
	global_store_dwordx4 v[22:23], v[0:3], off offset:3072 nt
	v_lshl_add_u64 v[22:23], v[22:23], 0, s[2:3]
	s_cbranch_scc1 .LBB0_1183
